# attention: early-exit vote (LDS flag read-back) skipped on the four diagonal tiles of each unit, where no exit is possible
# speedup vs baseline: 1.0059x; 1.0022x over previous
; __device__ __forceinline__ int tid_of(int wave) { return wave * 64 + lane_id(); }
; #define LAS __attribute__((address_space(3)))
; #define tid tid_of(wave)
; #define lane lane_id()
; __device__ __forceinline__ void attn_unit(LAS unsigned char* lds, const int wid, int b, int h, int qb, const bf16_t* __restrict__ Q, const bf16_t* __restrict__ K,
;                                           const bf16_t* __restrict__ V, const bf16_t* __restrict__ ZS, bf16_t* __restrict__ OG) {
;     const int tid = tid_of(wid), lane = tid & 63, r32 = lane & 31, hi = lane >> 5;
;     const size_t tok0 = (size_t)b * SEQ;
;     const int q0 = qb * 256, qw0 = q0 + 32 * wid, qabs = qw0 + r32;
;     bf16x8 qf[8];
;     { const bf16_t* qp = Q + (tok0 + qabs) * DM + h * HD + 8 * hi;
; #pragma unroll
;       for (int d0 = 0; d0 < 8; ++d0) qf[d0] = *(const bf16x8*)(qp + 16 * d0); }
;     f32x16 o[4];
; #pragma unroll
;     for (int c = 0; c < 4; ++c)
; #pragma unroll
;         for (int r = 0; r < 16; ++r) o[c][r] = 0.f;
;     bf16x8 pa[4];
; #pragma unroll
;     for (int s = 0; s < 4; ++s) pa[s] = (bf16x8){0, 0, 0, 0, 0, 0, 0, 0};
;     float carry = 0.f;
;     const int NT = (q0 + 256) / 64;
;     const int srow = tid >> 4, sch = (tid & 15) ^ (((srow & 3) << 2) | ((srow >> 2) & 3));
;     const bf16_t* kg = K + (tok0 + srow) * DM + h * HD + sch * 8;
;     const bf16_t* vg = V + (tok0 + srow) * DM + h * HD + sch * 8;
;     LAS unsigned char* ldsw = lds + wid * 1024;
;     ...
;     ATT_STAGE(NT - 1, 0, 32768);
;     asm volatile("s_waitcnt vmcnt(0)" ::: "memory");
;     __syncthreads();
;     ...
;     int kcur = 0, vprev = 2, vcur = 0, vnext = 1;
;     bool prev_valid = false;
;     for (int t = NT - 1; t >= 0; --t) {
.LBB0_594:
	s_ashr_i32 s4, s2, 7
	s_ashr_i32 s5, s4, 31
	s_lshl_b64 s[50:51], s[4:5], 12
	s_lshl_b32 s4, s2, 8
	s_and_b32 s63, s4, 0x700
	s_add_i32 s64, s63, s54
	v_or_b32_e32 v144, s64, v178
	v_lshl_add_u64 v[0:1], s[50:51], 0, v[144:145]
	s_lshl_b32 s4, s2, 4
	v_lshlrev_b64 v[0:1], 12, v[0:1]
	s_and_b32 s62, s4, 0x780
	v_lshl_add_u64 v[0:1], s[92:93], 0, v[0:1]
	s_lshl_b32 s42, s62, 1
	v_lshl_add_u64 v[0:1], v[0:1], 0, s[42:43]
	v_lshl_add_u64 v[0:1], v[0:1], 0, v[150:151]
	global_load_dwordx4 v[96:99], v[0:1], off
	global_load_dwordx4 v[100:103], v[0:1], off offset:32
	global_load_dwordx4 v[104:107], v[0:1], off offset:64
	global_load_dwordx4 v[108:111], v[0:1], off offset:96
	global_load_dwordx4 v[112:115], v[0:1], off offset:128
	global_load_dwordx4 v[116:119], v[0:1], off offset:160
	global_load_dwordx4 v[120:123], v[0:1], off offset:192
	global_load_dwordx4 v[124:127], v[0:1], off offset:224
	v_lshl_add_u64 v[0:1], s[50:51], 0, v[146:147]
	v_readlane_b32 s6, v248, 27
	s_add_i32 s4, s63, 0x100
	v_lshlrev_b64 v[0:1], 12, v[0:1]
	v_readlane_b32 s7, v248, 28
	s_lshr_b32 s4, s4, 6
	v_lshl_add_u64 v[2:3], s[44:45], 0, v[0:1]
	v_lshl_add_u64 v[0:1], s[6:7], 0, v[0:1]
	v_lshl_add_u64 v[2:3], v[2:3], 0, s[42:43]
	v_lshl_add_u64 v[0:1], v[0:1], 0, s[42:43]
	s_add_i32 s42, s4, -1
	v_lshl_add_u64 v[154:155], v[2:3], 0, v[152:153]
	s_lshl_b64 s[4:5], s[42:43], 18
	s_mov_b32 m0, s55
	v_lshl_add_u64 v[156:157], v[0:1], 0, v[152:153]
	v_lshl_add_u64 v[0:1], v[154:155], 0, s[4:5]
	global_load_lds_dwordx4 v[0:1], off
	v_lshl_add_u64 v[0:1], v[0:1], 0, s[48:49]
	s_mov_b32 m0, s59
	v_mov_b32_e32 v32, v145
	global_load_lds_dwordx4 v[0:1], off
	v_lshl_add_u64 v[0:1], v[156:157], 0, s[4:5]
	s_mov_b32 m0, s60
	s_bfe_u32 s4, s57, 0x30008
	global_load_lds_dwordx4 v[0:1], off
	v_lshl_add_u64 v[0:1], v[0:1], 0, s[48:49]
	s_mov_b32 m0, s61
	v_mov_b32_e32 v33, v145
	global_load_lds_dwordx4 v[0:1], off
	s_waitcnt vmcnt(0)
	v_mov_b32_e32 v46, v145
	v_mov_b32_e32 v47, v145
	s_lshl_b32 s5, s4, 2
	s_lshl_b32 s4, s4, 8
	v_mov_b32_e32 v34, v145
	v_mov_b32_e32 v35, v145
	v_mov_b32_e32 v36, v145
	v_mov_b32_e32 v37, v145
	v_mov_b32_e32 v38, v145
	v_mov_b32_e32 v39, v145
	v_mov_b32_e32 v40, v145
	v_mov_b32_e32 v41, v145
	v_mov_b32_e32 v42, v145
	v_mov_b32_e32 v43, v145
	v_mov_b32_e32 v44, v145
	v_mov_b32_e32 v45, v145
	v_mov_b64_e32 v[62:63], v[46:47]
	v_mov_b64_e32 v[0:1], v[32:33]
	v_mov_b64_e32 v[16:17], v[32:33]
	s_or_b32 s42, s5, 2
	s_or_b32 s65, s4, 0xc0
	s_or_b32 s66, s64, 31
	s_mov_b64 s[4:5], 0
	v_mov_b64_e32 v[60:61], v[44:45]
	v_mov_b64_e32 v[58:59], v[42:43]
	v_mov_b64_e32 v[56:57], v[40:41]
	v_mov_b64_e32 v[54:55], v[38:39]
	v_mov_b64_e32 v[52:53], v[36:37]
	v_mov_b64_e32 v[50:51], v[34:35]
	v_mov_b64_e32 v[48:49], v[32:33]
	v_mov_b64_e32 v[2:3], v[34:35]
	v_mov_b64_e32 v[4:5], v[36:37]
	v_mov_b64_e32 v[6:7], v[38:39]
	v_mov_b64_e32 v[8:9], v[40:41]
	v_mov_b64_e32 v[10:11], v[42:43]
	v_mov_b64_e32 v[12:13], v[44:45]
	v_mov_b64_e32 v[14:15], v[46:47]
	v_mov_b64_e32 v[18:19], v[34:35]
	v_mov_b64_e32 v[20:21], v[36:37]
	v_mov_b64_e32 v[22:23], v[38:39]
	v_mov_b64_e32 v[24:25], v[40:41]
	v_mov_b64_e32 v[26:27], v[42:43]
	v_mov_b64_e32 v[28:29], v[44:45]
	v_mov_b64_e32 v[30:31], v[46:47]
	s_mov_b32 s67, s43
	s_mov_b32 s74, 0
	s_mov_b32 s32, 0
	s_mov_b32 s6, 2
	s_mov_b32 s71, s43
	s_mov_b32 s72, 1
	v_mov_b32_e32 v158, 0
	v_mov_b32_e32 v140, 0
	v_mov_b32_e32 v141, v145
	v_mov_b32_e32 v142, v145
	v_mov_b32_e32 v143, v145
	v_mov_b32_e32 v136, 0
	v_mov_b32_e32 v137, v145
	v_mov_b32_e32 v138, v145
	v_mov_b32_e32 v139, v145
	v_mov_b32_e32 v132, 0
	v_mov_b32_e32 v133, v145
	v_mov_b32_e32 v134, v145
	v_mov_b32_e32 v135, v145
	v_mov_b32_e32 v128, 0
	v_mov_b32_e32 v129, v145
	v_mov_b32_e32 v130, v145
	v_mov_b32_e32 v131, v145
	s_waitcnt vmcnt(0) lgkmcnt(0)
	s_barrier
	s_mov_b32 s73, s6
	s_cmp_lg_u32 s65, 0
	s_mov_b64 s[6:7], -1
	s_cbranch_scc0 .LBB0_596

; __device__ __forceinline__ int lane_id() { return (int)__builtin_amdgcn_mbcnt_hi(~0u, __builtin_amdgcn_mbcnt_lo(~0u, 0u)); }
; #define LAS __attribute__((address_space(3)))
; __device__ __forceinline__ s16x4 vtr(const LAS unsigned char* p) { return __builtin_bit_cast(s16x4, __builtin_amdgcn_ds_read_tr16_b64_v4i16((LAS s16x4*)p)); }
; __device__ __forceinline__ void attn_unit(LAS unsigned char* lds, const int wid, int b, int h, int qb, const bf16_t* __restrict__ Q, const bf16_t* __restrict__ K,
;                                           const bf16_t* __restrict__ V, const bf16_t* __restrict__ ZS, bf16_t* __restrict__ OG) {
;     ...
;         prev_valid = valid;
;         asm volatile("s_waitcnt vmcnt(0)" ::: "memory");
;         __syncthreads();
;         kcur ^= 1; { const int tmp = vprev; vprev = vcur; vcur = vnext; vnext = tmp; }
;     }
;     { const LAS unsigned char* vbp = lds + 32768 + vprev * 16384;
; #pragma unroll
;       for (int c = 0; c < 4; ++c)
; #pragma unroll
;           for (int s = 0; s < 4; ++s) {
;               const s16x4 lo = vtr(vbp + 4096 * s + vbase[0] + vcq[c]);
;               const s16x4 hh = vtr(vbp + 4096 * s + vbase[1] + vcq[c]);
;               const bf16x8 vfr = (bf16x8){lo[0], lo[1], lo[2], lo[3], hh[0], hh[1], hh[2], hh[3]};
;               o[c] = __builtin_amdgcn_mfma_f32_32x32x16_bf16(pa[s], vfr, o[c], 0, 0, 0);
;           } }
;     {
;         int lane_e = lane_id(); asm volatile("" : "+v"(lane_e));
;         const int r32e = lane_e & 31, hie = lane_e >> 5, rowq = lane_e >> 3, c8 = (lane_e & 7) * 8;
;         LAS float* stg = (LAS float*)(lds + 81920 + wid * 8192);
;         const size_t gbase = (tok0 + qw0) * DM + h * HD + c8;
;         u32x4 zv[2][4];
; #pragma unroll
;         for (int ps = 0; ps < 2; ++ps)
; #pragma unroll
;             for (int j = 0; j < 4; ++j) zv[ps][j] = *(const u32x4*)(ZS + gbase + (size_t)(8 * j + rowq) * DM + 64 * ps);
.LBB0_609:
	s_waitcnt vmcnt(0)
	s_xor_b32 s67, s67, 1
	s_add_i32 s42, s42, -1
	s_sub_i32 s65, s65, 64
	v_cmp_gt_f32_e32 vcc, 0x43000000, v158
	s_lshr_b32 s98, s54, 3
	s_lshl_b32 s99, s67, 5
	s_add_i32 s98, s98, s99
	s_add_i32 s98, s98, 0x24000
	s_cmp_lg_u64 vcc, 0
	s_cselect_b32 s99, 1, 0
	s_xor_b32 s75, s99, 1
	s_add_i32 s74, s74, s75
	v_mov_b32_e32 v80, s98
	v_mov_b32_e32 v81, s99
	s_mov_b64 s[100:101], exec
	s_mov_b64 exec, 1
	ds_write_b32 v80, v81
	s_mov_b64 exec, s[100:101]
	s_cmpk_lg_i32 s65, 0xffc0
	s_waitcnt vmcnt(0) lgkmcnt(0)
	s_barrier
	s_cbranch_scc0 .LBB0_611
	s_add_i32 s32, s32, 1
	s_cmp_lt_u32 s32, 5
	s_cbranch_scc1 .Lvote_skip_a
	s_lshl_b32 s98, s67, 5
	s_add_i32 s98, s98, 0x24000
	v_mov_b32_e32 v80, s98
	ds_read_b128 v[84:87], v80
	ds_read_b128 v[88:91], v80 offset:16
	s_waitcnt lgkmcnt(0)
	v_or3_b32 v84, v84, v85, v86
	v_or3_b32 v88, v88, v89, v90
	v_or3_b32 v84, v84, v87, v91
	v_or_b32_e32 v84, v84, v88
	s_nop 0
	v_readfirstlane_b32 s99, v84
	s_cmp_eq_u32 s99, 0
	s_cbranch_scc1 .LBB0_611
.Lvote_skip_a:
	s_mov_b32 s6, s71
	s_mov_b32 s71, s72
	s_mov_b32 s72, s73
	s_mov_b64 s[4:5], s[52:53]
	s_mov_b32 s73, s6
	s_cmp_lg_u32 s65, 0
	s_mov_b64 s[6:7], -1
	s_cbranch_scc1 .LBB0_595
	s_branch .LBB0_596
.LBB0_611:
	s_lshl_b32 s4, s71, 14
	s_add_i32 s4, s4, 0
	v_add_u32_e32 v112, s4, v188
	v_add_u32_e32 v113, s4, v189
	v_add_u32_e32 v86, v112, v190
	v_add_u32_e32 v94, v113, v190
	ds_read_b64_tr_b16 v[82:83], v94 offset:34816
	ds_read_b64_tr_b16 v[80:81], v86 offset:32768
	ds_read_b64_tr_b16 v[84:85], v86 offset:36864
	ds_read_b64_tr_b16 v[88:89], v86 offset:40960
	ds_read_b64_tr_b16 v[92:93], v86 offset:45056
	ds_read_b64_tr_b16 v[86:87], v94 offset:38912
	ds_read_b64_tr_b16 v[90:91], v94 offset:43008
	ds_read_b64_tr_b16 v[94:95], v94 offset:47104
	s_waitcnt lgkmcnt(6)
	v_mfma_f32_32x32x16_bf16 v[32:47], v[64:67], v[80:83], v[32:47]
	v_add_u32_e32 v82, v112, v191
	v_add_u32_e32 v98, v113, v191
	v_add_u32_e32 v102, v112, v192
	v_add_u32_e32 v110, v113, v192
	v_mov_b32_e32 v144, v195
	s_add_u32 s4, s50, s64
	s_addc_u32 s5, s51, 0
	s_waitcnt lgkmcnt(2)
	v_mfma_f32_32x32x16_bf16 v[32:47], v[68:71], v[84:87], v[32:47]
	s_lshl_b64 s[4:5], s[4:5], 11
	s_xor_b32 s7, s63, 0xf00
	s_add_i32 s63, s7, s54
	s_lshl_b32 s42, s62, 1
	s_mov_b32 m0, s55
	s_mov_b32 s64, 1
	s_mov_b32 s6, 2
	s_waitcnt lgkmcnt(1)
	v_mfma_f32_32x32x16_bf16 v[32:47], v[72:75], v[88:91], v[32:47]
	ds_read_b64_tr_b16 v[80:81], v82 offset:32768
	ds_read_b64_tr_b16 v[84:85], v82 offset:36864
	ds_read_b64_tr_b16 v[88:89], v82 offset:40960
	ds_read_b64_tr_b16 v[96:97], v82 offset:45056
	s_or_b32 s65, s63, 31
	s_add_i32 s66, s7, 0xff
	s_mov_b32 s67, 0
	s_mov_b32 s74, 0
	s_mov_b32 s32, 0
	s_mov_b32 s71, 0
	s_waitcnt lgkmcnt(4)
	v_mfma_f32_32x32x16_bf16 v[32:47], v[76:79], v[92:95], v[32:47]
	ds_read_b64_tr_b16 v[82:83], v98 offset:34816
	ds_read_b64_tr_b16 v[86:87], v98 offset:38912
	ds_read_b64_tr_b16 v[90:91], v98 offset:43008
	ds_read_b64_tr_b16 v[98:99], v98 offset:47104
	ds_read_b64_tr_b16 v[92:93], v102 offset:32768
	ds_read_b64_tr_b16 v[100:101], v102 offset:36864
	ds_read_b64_tr_b16 v[104:105], v102 offset:40960
	ds_read_b64_tr_b16 v[108:109], v102 offset:45056
	ds_read_b64_tr_b16 v[94:95], v110 offset:34816
	ds_read_b64_tr_b16 v[102:103], v110 offset:38912
	ds_read_b64_tr_b16 v[106:107], v110 offset:43008
	ds_read_b64_tr_b16 v[110:111], v110 offset:47104
	s_waitcnt lgkmcnt(11)
	v_mfma_f32_32x32x16_bf16 v[48:63], v[64:67], v[80:83], v[48:63]
	v_add_u32_e32 v80, v112, v193
	v_add_u32_e32 v81, v113, v193
	ds_read_b64_tr_b16 v[112:113], v80 offset:32768
	ds_read_b64_tr_b16 v[116:117], v80 offset:36864
	ds_read_b64_tr_b16 v[120:121], v80 offset:40960
	ds_read_b64_tr_b16 v[124:125], v80 offset:45056
	ds_read_b64_tr_b16 v[114:115], v81 offset:34816
	ds_read_b64_tr_b16 v[118:119], v81 offset:38912
	ds_read_b64_tr_b16 v[122:123], v81 offset:43008
	ds_read_b64_tr_b16 v[126:127], v81 offset:47104
	v_mov_b32_e32 v81, s5
	v_lshlrev_b32_e32 v80, 3, v144
	s_waitcnt lgkmcnt(14)
	v_mfma_f32_32x32x16_bf16 v[48:63], v[68:71], v[84:87], v[48:63]
	v_and_b32_e32 v149, 56, v80
	v_or_b32_e32 v80, s4, v149
	v_ashrrev_i32_e32 v132, 3, v144
	v_or_b32_e32 v80, s62, v80
	v_lshlrev_b64 v[134:135], 1, v[80:81]
	v_ashrrev_i32_e32 v133, 31, v132
	v_lshl_add_u64 v[80:81], s[46:47], 0, v[134:135]
	v_lshlrev_b64 v[136:137], 12, v[132:133]
	v_lshl_add_u64 v[82:83], v[80:81], 0, v[136:137]
	v_mfma_f32_32x32x16_bf16 v[48:63], v[72:75], v[88:91], v[48:63]
	global_load_dwordx4 v[88:91], v[82:83], off
	v_add_u32_e32 v138, 8, v132
	v_ashrrev_i32_e32 v139, 31, v138
	v_lshlrev_b64 v[140:141], 12, v[138:139]
	v_lshl_add_u64 v[84:85], v[80:81], 0, v[140:141]
	v_add_u32_e32 v142, 16, v132
	v_add_u32_e32 v160, 24, v132
	s_waitcnt lgkmcnt(11)
	v_mfma_f32_32x32x16_bf16 v[0:15], v[64:67], v[92:95], v[0:15]
	global_load_dwordx4 v[92:95], v[84:85], off
	v_ashrrev_i32_e32 v143, 31, v142
	v_ashrrev_i32_e32 v161, 31, v160
	v_lshlrev_b64 v[158:159], 12, v[142:143]
	v_lshlrev_b64 v[162:163], 12, v[160:161]
	v_lshl_add_u64 v[86:87], v[80:81], 0, v[158:159]
	v_lshl_add_u64 v[80:81], v[80:81], 0, v[162:163]
	s_waitcnt lgkmcnt(10)
	v_mfma_f32_32x32x16_bf16 v[0:15], v[68:71], v[100:103], v[0:15]
	v_and_b32_e32 v133, 31, v144
	v_lshlrev_b32_e32 v133, 2, v133
	v_readlane_b32 s4, v248, 25
	v_readlane_b32 s5, v248, 26
	v_mov_b32_e32 v143, 0
	v_mov_b32_e32 v139, 0
	v_mfma_f32_32x32x16_bf16 v[48:63], v[76:79], v[96:99], v[48:63]
	global_load_dwordx4 v[96:99], v[82:83], off offset:128
	s_waitcnt lgkmcnt(9)
; #define LAS __attribute__((address_space(3)))
; __device__ __forceinline__ s16x4 vtr(const LAS unsigned char* p) { return __builtin_bit_cast(s16x4, __builtin_amdgcn_ds_read_tr16_b64_v4i16((LAS s16x4*)p)); }
; __device__ __forceinline__ unsigned pk_bf16(float lo, float hi) { return pg8::cvt_pk_bf16(lo, hi); }
; __device__ __forceinline__ float bf_lo(unsigned w) { return __uint_as_float(w << 16); }
; __device__ __forceinline__ float bf_hi(unsigned w) { return __uint_as_float(w & 0xffff0000u); }
; __device__ __forceinline__ void attn_unit(LAS unsigned char* lds, const int wid, int b, int h, int qb, const bf16_t* __restrict__ Q, const bf16_t* __restrict__ K,
;                                           const bf16_t* __restrict__ V, const bf16_t* __restrict__ ZS, bf16_t* __restrict__ OG) {
;     ...
;     { const LAS unsigned char* vbp = lds + 32768 + vprev * 16384;
; #pragma unroll
;       for (int c = 0; c < 4; ++c)
; #pragma unroll
;           for (int s = 0; s < 4; ++s) {
;               const s16x4 lo = vtr(vbp + 4096 * s + vbase[0] + vcq[c]);
;               const s16x4 hh = vtr(vbp + 4096 * s + vbase[1] + vcq[c]);
;               const bf16x8 vfr = (bf16x8){lo[0], lo[1], lo[2], lo[3], hh[0], hh[1], hh[2], hh[3]};
;               o[c] = __builtin_amdgcn_mfma_f32_32x32x16_bf16(pa[s], vfr, o[c], 0, 0, 0);
;           } }
;     ...
;         for (int ps = 0; ps < 2; ++ps) {
; #pragma unroll
;             for (int r = 0; r < 16; ++r) {
;                 stg[crow(r, hie) * 64 + r32e] = o[2 * ps][r];
;                 stg[crow(r, hie) * 64 + 32 + r32e] = o[2 * ps + 1][r];
;             }
;             asm volatile("s_waitcnt lgkmcnt(0)" ::: "memory");
; #pragma unroll
;             for (int j = 0; j < 4; ++j) {
;                 const f32x4 oa = *(const LAS f32x4*)(stg + (8 * j + rowq) * 64 + c8), ob = *(const LAS f32x4*)(stg + (8 * j + rowq) * 64 + c8 + 4);
;                 const u32x4 z = zv[ps][j];
;                 u32x4 w; w.x = pk_bf16(oa[0] * bf_lo(z.x), oa[1] * bf_hi(z.x)); w.y = pk_bf16(oa[2] * bf_lo(z.y), oa[3] * bf_hi(z.y));
;                 w.z = pk_bf16(ob[0] * bf_lo(z.z), ob[1] * bf_hi(z.z)); w.w = pk_bf16(ob[2] * bf_lo(z.w), ob[3] * bf_hi(z.w));
;                 *(u32x4*)(OG + gbase + (size_t)(8 * j + rowq) * DM + 64 * ps) = w;
;             }
;             asm volatile("s_waitcnt lgkmcnt(0)" ::: "memory");
;         }
	v_mfma_f32_32x32x16_bf16 v[0:15], v[72:75], v[104:107], v[0:15]
	global_load_dwordx4 v[100:103], v[84:85], off offset:128
	global_load_dwordx4 v[104:107], v[86:87], off
	s_nop 0
	global_load_dwordx4 v[84:87], v[86:87], off offset:128
	s_nop 0
	global_load_dwordx4 v[128:131], v[80:81], off
	s_nop 0
	global_load_dwordx4 v[80:83], v[80:81], off offset:128
	s_waitcnt lgkmcnt(8)
	v_mfma_f32_32x32x16_bf16 v[0:15], v[76:79], v[108:111], v[0:15]
	v_lshlrev_b32_e32 v110, 5, v144
	v_and_b32_e32 v110, 0xfffffc00, v110
	v_add3_u32 v110, s56, v133, v110
	ds_write2_b32 v110, v32, v48 offset1:32
	ds_write2_b32 v110, v33, v49 offset0:64 offset1:96
	ds_write2_b32 v110, v34, v50 offset0:128 offset1:160
	ds_write2_b32 v110, v35, v51 offset0:192 offset1:224
	v_add_u32_e32 v48, 0x800, v110
	v_add_u32_e32 v49, 0x1000, v110
	v_add_u32_e32 v50, 0x1800, v110
	v_lshl_add_u32 v108, v149, 2, s56
	ds_write2_b32 v48, v36, v52 offset1:32
	ds_write2_b32 v48, v37, v53 offset0:64 offset1:96
	ds_write2_b32 v48, v38, v54 offset0:128 offset1:160
	ds_write2_b32 v48, v39, v55 offset0:192 offset1:224
	ds_write2_b32 v49, v40, v56 offset1:32
	ds_write2_b32 v49, v41, v57 offset0:64 offset1:96
	ds_write2_b32 v49, v42, v58 offset0:128 offset1:160
	ds_write2_b32 v49, v43, v59 offset0:192 offset1:224
	ds_write2_b32 v50, v44, v60 offset1:32
	ds_write2_b32 v50, v45, v61 offset0:64 offset1:96
	ds_write2_b32 v50, v46, v62 offset0:128 offset1:160
	ds_write2_b32 v50, v47, v63 offset0:192 offset1:224
	v_lshl_add_u32 v109, v132, 8, v108
	s_waitcnt lgkmcnt(0)
	ds_read_b128 v[32:35], v109
	ds_read_b128 v[36:39], v109 offset:16
	v_lshl_add_u32 v51, v138, 8, v108
	v_lshl_add_u64 v[40:41], s[4:5], 0, v[134:135]
	s_waitcnt lgkmcnt(14)
	v_mfma_f32_32x32x16_bf16 v[16:31], v[64:67], v[112:115], v[16:31]
	v_lshl_add_u32 v52, v142, 8, v108
	v_lshl_add_u32 v53, v160, 8, v108
	v_or_b32_e32 v144, s63, v178
	v_mov_b32_e32 v149, v145
	s_add_i32 s4, s7, 0x100
	s_lshr_b32 s8, s4, 6
	v_mov_b32_e32 v142, 0
	v_mfma_f32_32x32x16_bf16 v[16:31], v[68:71], v[116:119], v[16:31]
	v_mov_b32_e32 v138, 0
	v_mov_b32_e32 v132, 0
	v_mov_b32_e32 v133, 0
	v_mov_b32_e32 v134, 0
	v_mov_b32_e32 v135, 0
	s_waitcnt vmcnt(7)
	v_lshlrev_b32_e32 v42, 16, v88
	s_waitcnt lgkmcnt(1)
	v_mul_f32_e32 v32, v32, v42
	v_and_b32_e32 v42, 0xffff0000, v88
	v_mul_f32_e32 v33, v33, v42
	v_cvt_pk_bf16_f32 v32, v32, v33
	v_lshlrev_b32_e32 v33, 16, v89
	v_mul_f32_e32 v33, v34, v33
	v_and_b32_e32 v34, 0xffff0000, v89
	v_mul_f32_e32 v34, v35, v34
	v_cvt_pk_bf16_f32 v33, v33, v34
	v_lshlrev_b32_e32 v34, 16, v90
	v_and_b32_e32 v35, 0xffff0000, v90
	s_waitcnt lgkmcnt(0)
	v_mul_f32_e32 v34, v36, v34
	v_mul_f32_e32 v35, v37, v35
	v_cvt_pk_bf16_f32 v34, v34, v35
	v_lshlrev_b32_e32 v35, 16, v91
	v_and_b32_e32 v36, 0xffff0000, v91
	v_mul_f32_e32 v35, v38, v35
	v_mul_f32_e32 v36, v39, v36
	v_cvt_pk_bf16_f32 v35, v35, v36
	ds_read_b128 v[36:39], v51
	v_lshl_add_u64 v[42:43], v[40:41], 0, v[136:137]
	s_waitcnt vmcnt(6)
	v_lshlrev_b32_e32 v44, 16, v92
	global_store_dwordx4 v[42:43], v[32:35], off sc1
	ds_read_b128 v[32:35], v51 offset:16
	s_waitcnt lgkmcnt(1)
	v_mul_f32_e32 v36, v36, v44
	v_and_b32_e32 v44, 0xffff0000, v92
	v_mul_f32_e32 v37, v37, v44
	v_cvt_pk_bf16_f32 v36, v36, v37
	v_lshlrev_b32_e32 v37, 16, v93
	v_mul_f32_e32 v37, v38, v37
	v_and_b32_e32 v38, 0xffff0000, v93
	v_mul_f32_e32 v38, v39, v38
	v_cvt_pk_bf16_f32 v37, v37, v38
	v_lshlrev_b32_e32 v38, 16, v94
	s_waitcnt lgkmcnt(0)
	v_mul_f32_e32 v32, v32, v38
	v_and_b32_e32 v38, 0xffff0000, v94
	v_mul_f32_e32 v33, v33, v38
	v_cvt_pk_bf16_f32 v38, v32, v33
	v_lshlrev_b32_e32 v32, 16, v95
	v_and_b32_e32 v33, 0xffff0000, v95
	v_mul_f32_e32 v32, v34, v32
	v_mul_f32_e32 v33, v35, v33
	v_cvt_pk_bf16_f32 v39, v32, v33
	ds_read_b128 v[32:35], v52
	v_lshl_add_u64 v[44:45], v[40:41], 0, v[140:141]
	s_waitcnt vmcnt(4)
	v_lshlrev_b32_e32 v46, 16, v104
	global_store_dwordx4 v[44:45], v[36:39], off sc1
	ds_read_b128 v[36:39], v52 offset:16
	s_waitcnt lgkmcnt(1)
	v_mul_f32_e32 v32, v32, v46
	v_and_b32_e32 v46, 0xffff0000, v104
	v_mul_f32_e32 v33, v33, v46
	v_cvt_pk_bf16_f32 v32, v32, v33
	v_lshlrev_b32_e32 v33, 16, v105
	v_mul_f32_e32 v33, v34, v33
	v_and_b32_e32 v34, 0xffff0000, v105
	v_mul_f32_e32 v34, v35, v34
	v_cvt_pk_bf16_f32 v33, v33, v34
	v_lshlrev_b32_e32 v34, 16, v106
	v_and_b32_e32 v35, 0xffff0000, v106
	s_waitcnt lgkmcnt(0)
	v_mul_f32_e32 v34, v36, v34
	v_mul_f32_e32 v35, v37, v35
	v_cvt_pk_bf16_f32 v34, v34, v35
	v_lshlrev_b32_e32 v35, 16, v107
	v_and_b32_e32 v36, 0xffff0000, v107
	v_mul_f32_e32 v35, v38, v35
	v_mul_f32_e32 v36, v39, v36
	v_cvt_pk_bf16_f32 v35, v35, v36
	ds_read_b128 v[36:39], v53
	v_mfma_f32_32x32x16_bf16 v[16:31], v[72:75], v[120:123], v[16:31]
	v_lshl_add_u64 v[46:47], v[40:41], 0, v[158:159]
	s_waitcnt vmcnt(3)
	v_lshlrev_b32_e32 v54, 16, v128
	global_store_dwordx4 v[46:47], v[32:35], off sc1
	ds_read_b128 v[32:35], v53 offset:16
	s_waitcnt lgkmcnt(1)
	v_mul_f32_e32 v36, v36, v54
	v_and_b32_e32 v54, 0xffff0000, v128
	v_mul_f32_e32 v37, v37, v54
	v_cvt_pk_bf16_f32 v36, v36, v37
	v_lshlrev_b32_e32 v37, 16, v129
	v_mul_f32_e32 v37, v38, v37
	v_and_b32_e32 v38, 0xffff0000, v129
	v_mfma_f32_32x32x16_bf16 v[16:31], v[76:79], v[124:127], v[16:31]
	v_mul_f32_e32 v38, v39, v38
	v_cvt_pk_bf16_f32 v37, v37, v38
	v_lshlrev_b32_e32 v38, 16, v130
	s_waitcnt lgkmcnt(0)
	v_mul_f32_e32 v32, v32, v38
	v_and_b32_e32 v38, 0xffff0000, v130
	v_mul_f32_e32 v33, v33, v38
	v_cvt_pk_bf16_f32 v38, v32, v33
	v_lshlrev_b32_e32 v32, 16, v131
	v_and_b32_e32 v33, 0xffff0000, v131
	v_mul_f32_e32 v32, v34, v32
	v_mul_f32_e32 v33, v35, v33
	v_cvt_pk_bf16_f32 v39, v32, v33
	v_lshl_add_u64 v[32:33], v[40:41], 0, v[162:163]
	global_store_dwordx4 v[32:33], v[36:39], off sc1
	s_waitcnt lgkmcnt(0)
; #define LAS __attribute__((address_space(3)))
; __device__ __forceinline__ unsigned pk_bf16(float lo, float hi) { return pg8::cvt_pk_bf16(lo, hi); }
; #define tid tid_of(wave)
; __device__ __forceinline__ void attn_unit(LAS unsigned char* lds, const int wid, int b, int h, int qb, const bf16_t* __restrict__ Q, const bf16_t* __restrict__ K,
;                                           const bf16_t* __restrict__ V, const bf16_t* __restrict__ ZS, bf16_t* __restrict__ OG) {
;     ...
;     { const bf16_t* qp = Q + (tok0 + qabs) * DM + h * HD + 8 * hi;
; #pragma unroll
;       for (int d0 = 0; d0 < 8; ++d0) qf[d0] = *(const bf16x8*)(qp + 16 * d0); }
;     f32x16 o[4];
; #pragma unroll
;     for (int c = 0; c < 4; ++c)
; #pragma unroll
;         for (int r = 0; r < 16; ++r) o[c][r] = 0.f;
;     bf16x8 pa[4];
; #pragma unroll
;     for (int s = 0; s < 4; ++s) pa[s] = (bf16x8){0, 0, 0, 0, 0, 0, 0, 0};
;     float carry = 0.f;
;     const int NT = (q0 + 256) / 64;
;     const int srow = tid >> 4, sch = (tid & 15) ^ (((srow & 3) << 2) | ((srow >> 2) & 3));
;     const bf16_t* kg = K + (tok0 + srow) * DM + h * HD + sch * 8;
;     const bf16_t* vg = V + (tok0 + srow) * DM + h * HD + sch * 8;
;     LAS unsigned char* ldsw = lds + wid * 1024;
;     ...
;     ATT_STAGE(NT - 1, 0, 32768);
;     asm volatile("s_waitcnt vmcnt(0)" ::: "memory");
;     __syncthreads();
;     ...
;         for (int ps = 0; ps < 2; ++ps) {
; #pragma unroll
;             for (int r = 0; r < 16; ++r) {
;                 stg[crow(r, hie) * 64 + r32e] = o[2 * ps][r];
;                 stg[crow(r, hie) * 64 + 32 + r32e] = o[2 * ps + 1][r];
;             }
;             asm volatile("s_waitcnt lgkmcnt(0)" ::: "memory");
; #pragma unroll
;             for (int j = 0; j < 4; ++j) {
;                 const f32x4 oa = *(const LAS f32x4*)(stg + (8 * j + rowq) * 64 + c8), ob = *(const LAS f32x4*)(stg + (8 * j + rowq) * 64 + c8 + 4);
;                 const u32x4 z = zv[ps][j];
;                 u32x4 w; w.x = pk_bf16(oa[0] * bf_lo(z.x), oa[1] * bf_hi(z.x)); w.y = pk_bf16(oa[2] * bf_lo(z.y), oa[3] * bf_hi(z.y));
;                 w.z = pk_bf16(ob[0] * bf_lo(z.z), ob[1] * bf_hi(z.z)); w.w = pk_bf16(ob[2] * bf_lo(z.w), ob[3] * bf_hi(z.w));
;                 *(u32x4*)(OG + gbase + (size_t)(8 * j + rowq) * DM + 64 * ps) = w;
;             }
;             asm volatile("s_waitcnt lgkmcnt(0)" ::: "memory");
;         }
	ds_write2_b32 v110, v0, v16 offset1:32
	ds_write2_b32 v110, v1, v17 offset0:64 offset1:96
	ds_write2_b32 v110, v2, v18 offset0:128 offset1:160
	ds_write2_b32 v110, v3, v19 offset0:192 offset1:224
	ds_write2_b32 v48, v4, v20 offset1:32
	ds_write2_b32 v48, v5, v21 offset0:64 offset1:96
	ds_write2_b32 v48, v6, v22 offset0:128 offset1:160
	ds_write2_b32 v48, v7, v23 offset0:192 offset1:224
	ds_write2_b32 v49, v8, v24 offset1:32
	ds_write2_b32 v49, v9, v25 offset0:64 offset1:96
	ds_write2_b32 v49, v10, v26 offset0:128 offset1:160
	ds_write2_b32 v49, v11, v27 offset0:192 offset1:224
	ds_write2_b32 v50, v12, v28 offset1:32
	ds_write2_b32 v50, v13, v29 offset0:64 offset1:96
	ds_write2_b32 v50, v14, v30 offset0:128 offset1:160
	ds_write2_b32 v50, v15, v31 offset0:192 offset1:224
	s_waitcnt lgkmcnt(0)
	ds_read_b128 v[0:3], v109
	ds_read_b128 v[4:7], v109 offset:16
	v_lshlrev_b32_e32 v8, 16, v96
	v_mov_b32_e32 v34, v145
	v_mov_b32_e32 v35, v145
	s_waitcnt lgkmcnt(1)
	v_mul_f32_e32 v0, v0, v8
	v_and_b32_e32 v8, 0xffff0000, v96
	v_mul_f32_e32 v1, v1, v8
	v_cvt_pk_bf16_f32 v0, v0, v1
	v_lshlrev_b32_e32 v1, 16, v97
	v_mul_f32_e32 v1, v2, v1
	v_and_b32_e32 v2, 0xffff0000, v97
	v_mul_f32_e32 v2, v3, v2
	v_cvt_pk_bf16_f32 v1, v1, v2
	v_lshlrev_b32_e32 v2, 16, v98
	v_and_b32_e32 v3, 0xffff0000, v98
	s_waitcnt lgkmcnt(0)
	v_mul_f32_e32 v2, v4, v2
	v_mul_f32_e32 v3, v5, v3
	v_cvt_pk_bf16_f32 v2, v2, v3
	v_lshlrev_b32_e32 v3, 16, v99
	v_and_b32_e32 v4, 0xffff0000, v99
	v_mul_f32_e32 v3, v6, v3
	v_mul_f32_e32 v4, v7, v4
	v_cvt_pk_bf16_f32 v3, v3, v4
	ds_read_b128 v[4:7], v51
	v_lshlrev_b32_e32 v8, 16, v100
	global_store_dwordx4 v[42:43], v[0:3], off offset:128 sc1
	ds_read_b128 v[0:3], v51 offset:16
	v_mov_b32_e32 v36, v145
	s_waitcnt lgkmcnt(1)
	v_mul_f32_e32 v4, v4, v8
	v_and_b32_e32 v8, 0xffff0000, v100
	v_mul_f32_e32 v5, v5, v8
	v_cvt_pk_bf16_f32 v4, v4, v5
	v_lshlrev_b32_e32 v5, 16, v101
	v_mul_f32_e32 v5, v6, v5
	v_and_b32_e32 v6, 0xffff0000, v101
	v_mul_f32_e32 v6, v7, v6
	v_cvt_pk_bf16_f32 v5, v5, v6
	v_lshlrev_b32_e32 v6, 16, v102
	s_waitcnt lgkmcnt(0)
	v_mul_f32_e32 v0, v0, v6
	v_and_b32_e32 v6, 0xffff0000, v102
	v_mul_f32_e32 v1, v1, v6
	v_cvt_pk_bf16_f32 v6, v0, v1
	v_lshlrev_b32_e32 v0, 16, v103
	v_and_b32_e32 v1, 0xffff0000, v103
	v_mul_f32_e32 v0, v2, v0
	v_mul_f32_e32 v1, v3, v1
	v_cvt_pk_bf16_f32 v7, v0, v1
	ds_read_b128 v[0:3], v52
	v_lshlrev_b32_e32 v8, 16, v84
	global_store_dwordx4 v[44:45], v[4:7], off offset:128 sc1
	ds_read_b128 v[4:7], v52 offset:16
	v_mov_b32_e32 v37, v145
	s_waitcnt lgkmcnt(1)
	v_mul_f32_e32 v0, v0, v8
	v_and_b32_e32 v8, 0xffff0000, v84
	v_mul_f32_e32 v1, v1, v8
	v_cvt_pk_bf16_f32 v0, v0, v1
	v_lshlrev_b32_e32 v1, 16, v85
	v_mul_f32_e32 v1, v2, v1
	v_and_b32_e32 v2, 0xffff0000, v85
	v_mul_f32_e32 v2, v3, v2
	v_cvt_pk_bf16_f32 v1, v1, v2
	v_lshlrev_b32_e32 v2, 16, v86
	v_and_b32_e32 v3, 0xffff0000, v86
	s_waitcnt lgkmcnt(0)
	v_mul_f32_e32 v2, v4, v2
	v_mul_f32_e32 v3, v5, v3
	v_cvt_pk_bf16_f32 v2, v2, v3
	v_lshlrev_b32_e32 v3, 16, v87
	v_and_b32_e32 v4, 0xffff0000, v87
	v_mul_f32_e32 v3, v6, v3
	v_mul_f32_e32 v4, v7, v4
	v_cvt_pk_bf16_f32 v3, v3, v4
	ds_read_b128 v[4:7], v53
	s_waitcnt vmcnt(6)
	v_lshlrev_b32_e32 v8, 16, v80
	global_store_dwordx4 v[46:47], v[0:3], off offset:128 sc1
	ds_read_b128 v[0:3], v53 offset:16
	v_mov_b32_e32 v46, v145
	s_waitcnt lgkmcnt(1)
	v_mul_f32_e32 v4, v4, v8
	v_and_b32_e32 v8, 0xffff0000, v80
	v_mul_f32_e32 v5, v5, v8
	v_cvt_pk_bf16_f32 v4, v4, v5
	v_lshlrev_b32_e32 v5, 16, v81
	v_mul_f32_e32 v5, v6, v5
	v_and_b32_e32 v6, 0xffff0000, v81
	v_mul_f32_e32 v6, v7, v6
	v_cvt_pk_bf16_f32 v5, v5, v6
	v_lshlrev_b32_e32 v6, 16, v82
	s_waitcnt lgkmcnt(0)
	v_mul_f32_e32 v0, v0, v6
	v_and_b32_e32 v6, 0xffff0000, v82
	v_mul_f32_e32 v1, v1, v6
	v_cvt_pk_bf16_f32 v6, v0, v1
	v_lshlrev_b32_e32 v0, 16, v83
	v_and_b32_e32 v1, 0xffff0000, v83
	v_mul_f32_e32 v0, v2, v0
	v_mul_f32_e32 v1, v3, v1
	v_cvt_pk_bf16_f32 v7, v0, v1
	v_lshl_add_u64 v[0:1], s[50:51], 0, v[144:145]
	v_lshlrev_b64 v[0:1], 12, v[0:1]
	v_lshl_add_u64 v[0:1], s[92:93], 0, v[0:1]
	v_lshl_add_u64 v[0:1], v[0:1], 0, s[42:43]
	global_store_dwordx4 v[32:33], v[4:7], off offset:128 sc1
	v_lshl_add_u64 v[0:1], v[0:1], 0, v[148:149]
	s_waitcnt lgkmcnt(0)
	s_barrier
	global_load_dwordx4 v[96:99], v[0:1], off
	global_load_dwordx4 v[100:103], v[0:1], off offset:32
	global_load_dwordx4 v[104:107], v[0:1], off offset:64
	global_load_dwordx4 v[108:111], v[0:1], off offset:96
	global_load_dwordx4 v[112:115], v[0:1], off offset:128
	global_load_dwordx4 v[116:119], v[0:1], off offset:160
	global_load_dwordx4 v[120:123], v[0:1], off offset:192
	global_load_dwordx4 v[124:127], v[0:1], off offset:224
	s_add_i32 s42, s8, -1
	s_lshl_b64 s[4:5], s[42:43], 18
	v_lshl_add_u64 v[0:1], v[154:155], 0, s[4:5]
	global_load_lds_dwordx4 v[0:1], off
	v_lshl_add_u64 v[0:1], v[0:1], 0, s[48:49]
	s_mov_b32 m0, s59
	v_mov_b32_e32 v32, v145
	global_load_lds_dwordx4 v[0:1], off
	v_lshl_add_u64 v[0:1], v[156:157], 0, s[4:5]
	s_mov_b32 m0, s60
	v_mov_b32_e32 v33, v145
	global_load_lds_dwordx4 v[0:1], off
	v_lshl_add_u64 v[0:1], v[0:1], 0, s[48:49]
	s_mov_b32 m0, s61
	v_mov_b32_e32 v47, v145
	global_load_lds_dwordx4 v[0:1], off
	s_waitcnt vmcnt(0)
	v_mov_b32_e32 v38, v145
	v_mov_b32_e32 v39, v145
	v_mov_b32_e32 v40, v145
	v_mov_b32_e32 v41, v145
	v_mov_b32_e32 v42, v145
	v_mov_b32_e32 v43, v145
	v_mov_b32_e32 v44, v145
	v_mov_b32_e32 v45, v145
	v_mov_b64_e32 v[62:63], v[46:47]
	v_mov_b64_e32 v[0:1], v[32:33]
	v_mov_b64_e32 v[16:17], v[32:33]
	s_add_i32 s42, s8, -2
	v_mov_b32_e32 v158, 0
	s_mov_b64 s[4:5], 0
	v_mov_b32_e32 v140, 0
	v_mov_b32_e32 v141, 0
	v_mov_b32_e32 v136, 0
	v_mov_b32_e32 v137, 0
	v_mov_b32_e32 v128, 0
	v_mov_b32_e32 v129, 0
	v_mov_b32_e32 v130, 0
	v_mov_b32_e32 v131, 0
	v_mov_b64_e32 v[60:61], v[44:45]
	v_mov_b64_e32 v[58:59], v[42:43]
	v_mov_b64_e32 v[56:57], v[40:41]
	v_mov_b64_e32 v[54:55], v[38:39]
	v_mov_b64_e32 v[52:53], v[36:37]
	v_mov_b64_e32 v[50:51], v[34:35]
	v_mov_b64_e32 v[48:49], v[32:33]
	v_mov_b64_e32 v[2:3], v[34:35]
	v_mov_b64_e32 v[4:5], v[36:37]
	v_mov_b64_e32 v[6:7], v[38:39]
	v_mov_b64_e32 v[8:9], v[40:41]
	v_mov_b64_e32 v[10:11], v[42:43]
	v_mov_b64_e32 v[12:13], v[44:45]
	v_mov_b64_e32 v[14:15], v[46:47]
	v_mov_b64_e32 v[18:19], v[34:35]
	v_mov_b64_e32 v[20:21], v[36:37]
	v_mov_b64_e32 v[22:23], v[38:39]
	v_mov_b64_e32 v[24:25], v[40:41]
	v_mov_b64_e32 v[26:27], v[42:43]
	v_mov_b64_e32 v[28:29], v[44:45]
	v_mov_b64_e32 v[30:31], v[46:47]
	s_waitcnt vmcnt(0) lgkmcnt(0)
	s_barrier
	s_mov_b32 s72, s6
	s_cmp_lg_u32 s42, -1
	s_mov_b64 s[6:7], -1
	s_cbranch_scc0 .LBB0_613

; __device__ __forceinline__ void attn_unit(LAS unsigned char* lds, const int wid, int b, int h, int qb, const bf16_t* __restrict__ Q, const bf16_t* __restrict__ K,
;                                           const bf16_t* __restrict__ V, const bf16_t* __restrict__ ZS, bf16_t* __restrict__ OG) {
;     ...
;         prev_valid = valid;
;         asm volatile("s_waitcnt vmcnt(0)" ::: "memory");
;         __syncthreads();
;         kcur ^= 1; { const int tmp = vprev; vprev = vcur; vcur = vnext; vnext = tmp; }
.LBB0_626:
	s_waitcnt vmcnt(0)
	s_xor_b32 s67, s67, 1
	s_add_i32 s42, s42, -1
	s_sub_i32 s66, s66, 64
	v_cmp_gt_f32_e32 vcc, 0x43000000, v158
	s_lshr_b32 s98, s54, 3
	s_lshl_b32 s99, s67, 5
	s_add_i32 s98, s98, s99
	s_add_i32 s98, s98, 0x24000
	s_cmp_lg_u64 vcc, 0
	s_cselect_b32 s99, 1, 0
	s_xor_b32 s75, s99, 1
	s_add_i32 s74, s74, s75
	v_mov_b32_e32 v80, s98
	v_mov_b32_e32 v81, s99
	s_mov_b64 s[100:101], exec
	s_mov_b64 exec, 1
	ds_write_b32 v80, v81
	s_mov_b64 exec, s[100:101]
	s_cmp_lg_u32 s42, -2
	s_waitcnt vmcnt(0) lgkmcnt(0)
	s_barrier
	s_cbranch_scc0 .LBB0_593
	s_add_i32 s32, s32, 1
	s_cmp_lt_u32 s32, 5
	s_cbranch_scc1 .Lvote_skip_b
	s_lshl_b32 s98, s67, 5
	s_add_i32 s98, s98, 0x24000
	v_mov_b32_e32 v80, s98
	ds_read_b128 v[84:87], v80
	ds_read_b128 v[88:91], v80 offset:16
	s_waitcnt lgkmcnt(0)
	v_or3_b32 v84, v84, v85, v86
	v_or3_b32 v88, v88, v89, v90
	v_or3_b32 v84, v84, v87, v91
	v_or_b32_e32 v84, v84, v88
	s_nop 0
	v_readfirstlane_b32 s99, v84
	s_cmp_eq_u32 s99, 0
	s_cbranch_scc1 .LBB0_593
.Lvote_skip_b:
	s_mov_b32 s6, s71
	s_mov_b32 s71, s64
	s_mov_b32 s64, s72
	s_mov_b64 s[4:5], s[52:53]
	s_mov_b32 s72, s6
	s_cmp_lg_u32 s42, -1
	s_mov_b64 s[6:7], -1
	s_cbranch_scc1 .LBB0_612
	s_branch .LBB0_613
